# v46 + tighter spin polls: s_sleep 1 -> s_sleep 0 in the 57 spin loops (grid barrier polls)
# speedup vs baseline: 1.0058x; 1.0058x over previous
.LBB0_158:
	flat_load_dword v26, v[2:3] offset:1024 sc1
	flat_load_dword v25, v[2:3] offset:1280 sc1
	flat_load_dword v24, v[2:3] offset:1536 sc1
	flat_load_dword v23, v[2:3] offset:1792 sc1
	flat_load_dword v22, v[2:3] offset:2048 sc1
	flat_load_dword v21, v[2:3] offset:2304 sc1
	flat_load_dword v20, v[2:3] offset:2560 sc1
	flat_load_dword v19, v[2:3] offset:2816 sc1
	flat_load_dword v18, v[2:3] offset:3072 sc1
	flat_load_dword v17, v[2:3] offset:3328 sc1
	flat_load_dword v16, v[2:3] offset:3584 sc1
	flat_load_dword v15, v[2:3] offset:3840 sc1
	flat_load_dword v14, v[4:5] sc1
	flat_load_dword v13, v[6:7] sc1
	flat_load_dword v12, v[8:9] sc1
	flat_load_dword v1, v[10:11] sc1
	s_waitcnt vmcnt(0) lgkmcnt(0)
	v_add_u32_e32 v27, v25, v26
	v_add_u32_e32 v27, v27, v24
	v_add_u32_e32 v27, v27, v23
	v_add_u32_e32 v27, v27, v22
	v_add_u32_e32 v27, v27, v21
	v_add_u32_e32 v27, v27, v20
	v_add_u32_e32 v27, v27, v19
	v_add_u32_e32 v27, v27, v18
	v_add_u32_e32 v27, v27, v17
	v_add_u32_e32 v27, v27, v16
	v_add_u32_e32 v27, v27, v15
	v_add_u32_e32 v27, v27, v14
	v_add_u32_e32 v27, v27, v13
	v_add_u32_e32 v27, v27, v12
	v_add_u32_e32 v27, v27, v1
	v_cmp_ne_u32_e32 vcc, s0, v27
	s_or_b64 s[8:9], s[8:9], exec
	s_or_b64 s[6:7], s[6:7], exec
	s_and_saveexec_b64 s[10:11], vcc
	s_cbranch_execz .LBB0_157
	s_and_b32 s16, s1, 0xff
	s_mov_b64 s[14:15], -1
	s_cmp_eq_u32 s16, 0
	s_mov_b64 s[18:19], -1
	s_mov_b64 s[16:17], -1
	s_sleep 0
	s_cbranch_scc1 .LBB0_161
	s_and_saveexec_b64 s[20:21], s[18:19]
	s_cbranch_execz .LBB0_156
	s_branch .LBB0_164

.LBB0_172:
	s_and_b32 s1, s0, 0xff
	s_mov_b64 s[16:17], -1
	s_cmp_lg_u32 s1, 0
	s_mov_b64 s[18:19], -1
	s_sleep 0
	s_cbranch_scc1 .LBB0_176
	v_mov_b64_e32 v[2:3], s[38:39]
	flat_load_dword v2, v[2:3] offset:512 sc1
	s_mov_b64 s[18:19], 0
	s_mov_b64 s[20:21], -1
	s_waitcnt vmcnt(0) lgkmcnt(0)
	v_cmp_eq_u32_e32 vcc, 0, v2
	s_and_saveexec_b64 s[22:23], vcc
	s_cmp_lt_u32 s0, 0x40001
	s_cselect_b64 s[18:19], -1, 0
	s_xor_b64 s[20:21], exec, -1
	s_and_b64 s[18:19], s[18:19], exec
	s_or_b64 exec, exec, s[22:23]

.LBB0_186:
	s_and_b32 s1, s0, 0xff
	s_cmp_lg_u32 s1, 0
	s_mov_b64 s[18:19], -1
	s_sleep 0
	s_cbranch_scc0 .LBB0_188
	s_mov_b64 s[20:21], -1
	s_and_saveexec_b64 s[22:23], s[18:19]
	s_cbranch_execz .LBB0_185
	s_branch .LBB0_191

.LBB0_367:
	s_and_b32 s1, s0, 0xff
	s_cmp_lg_u32 s1, 0
	s_mov_b64 s[20:21], -1
	s_sleep 0
	s_cbranch_scc0 .LBB0_369
	s_mov_b64 s[22:23], -1
	s_and_saveexec_b64 s[24:25], s[20:21]
	s_cbranch_execz .LBB0_366
	s_branch .LBB0_372

.LBB0_534:
	v_mov_b64_e32 v[2:3], s[38:39]
	flat_load_dword v17, v[2:3] offset:1024 sc1
	flat_load_dword v16, v[2:3] offset:1280 sc1
	flat_load_dword v15, v[2:3] offset:1536 sc1
	flat_load_dword v14, v[2:3] offset:1792 sc1
	flat_load_dword v13, v[2:3] offset:2048 sc1
	flat_load_dword v12, v[2:3] offset:2304 sc1
	flat_load_dword v11, v[2:3] offset:2560 sc1
	flat_load_dword v10, v[2:3] offset:2816 sc1
	flat_load_dword v9, v[2:3] offset:3072 sc1
	flat_load_dword v8, v[2:3] offset:3328 sc1
	flat_load_dword v7, v[2:3] offset:3584 sc1
	s_nop 0
	flat_load_dword v2, v[2:3] offset:3840 sc1
	v_mov_b64_e32 v[4:5], s[2:3]
	flat_load_dword v3, v[4:5] sc1
	v_mov_b64_e32 v[4:5], s[4:5]
	v_mov_b64_e32 v[18:19], s[6:7]
	flat_load_dword v4, v[4:5] sc1
	s_nop 0
	flat_load_dword v5, v[18:19] sc1
	v_mov_b64_e32 v[18:19], s[8:9]
	flat_load_dword v6, v[18:19] sc1
	s_waitcnt vmcnt(0) lgkmcnt(0)
	v_add_u32_e32 v18, v16, v17
	v_add_u32_e32 v18, v18, v15
	v_add_u32_e32 v18, v18, v14
	v_add_u32_e32 v18, v18, v13
	v_add_u32_e32 v18, v18, v12
	v_add_u32_e32 v18, v18, v11
	v_add_u32_e32 v18, v18, v10
	v_add_u32_e32 v18, v18, v9
	v_add_u32_e32 v18, v18, v8
	v_add_u32_e32 v18, v18, v7
	v_add_u32_e32 v18, v18, v2
	v_add_u32_e32 v18, v18, v3
	v_add_u32_e32 v18, v18, v4
	v_add_u32_e32 v18, v18, v5
	v_add_u32_e32 v18, v18, v6
	v_cmp_ne_u32_e32 vcc, s0, v18
	s_or_b64 s[18:19], s[18:19], exec
	s_or_b64 s[16:17], s[16:17], exec
	s_and_saveexec_b64 s[20:21], vcc
	s_cbranch_execz .LBB0_533
	s_and_b32 s24, s1, 0xff
	s_mov_b64 s[22:23], -1
	s_cmp_eq_u32 s24, 0
	s_mov_b64 s[26:27], -1
	s_mov_b64 s[24:25], -1
	s_sleep 0
	s_cbranch_scc1 .LBB0_537
	s_and_saveexec_b64 s[28:29], s[26:27]
	s_cbranch_execz .LBB0_532
	s_branch .LBB0_540

.LBB0_548:
	s_and_b32 s1, s0, 0xff
	s_mov_b64 s[16:17], -1
	s_cmp_lg_u32 s1, 0
	s_mov_b64 s[18:19], -1
	s_sleep 0
	s_cbranch_scc1 .LBB0_552
	v_mov_b64_e32 v[4:5], s[38:39]
	flat_load_dword v2, v[4:5] offset:512 sc1
	s_mov_b64 s[18:19], 0
	s_mov_b64 s[20:21], -1
	s_waitcnt vmcnt(0) lgkmcnt(0)
	v_cmp_eq_u32_e32 vcc, 0, v2
	s_and_saveexec_b64 s[22:23], vcc
	s_cmp_lt_u32 s0, 0x40001
	s_cselect_b64 s[18:19], -1, 0
	s_xor_b64 s[20:21], exec, -1
	s_and_b64 s[18:19], s[18:19], exec
	s_or_b64 exec, exec, s[22:23]

.LBB0_562:
	s_and_b32 s1, s0, 0xff
	s_mov_b64 s[18:19], -1
	s_cmp_lg_u32 s1, 0
	s_mov_b64 s[22:23], -1
	s_sleep 0
	s_cbranch_scc0 .LBB0_564
	s_and_saveexec_b64 s[24:25], s[22:23]
	s_cbranch_execz .LBB0_561
	s_branch .LBB0_567

.LBB0_612:
	s_and_b32 s1, s0, 0xff
	s_mov_b64 s[16:17], -1
	s_cmp_lg_u32 s1, 0
	s_mov_b64 s[20:21], -1
	s_sleep 0
	s_cbranch_scc0 .LBB0_614
	s_and_saveexec_b64 s[22:23], s[20:21]
	s_cbranch_execz .LBB0_611
	s_branch .LBB0_617

.LBB0_913:
	v_mov_b64_e32 v[2:3], s[2:3]
	flat_load_dword v17, v[2:3] offset:1024 sc1
	flat_load_dword v16, v[2:3] offset:1280 sc1
	flat_load_dword v15, v[2:3] offset:1536 sc1
	flat_load_dword v14, v[2:3] offset:1792 sc1
	flat_load_dword v13, v[2:3] offset:2048 sc1
	flat_load_dword v12, v[2:3] offset:2304 sc1
	flat_load_dword v11, v[2:3] offset:2560 sc1
	flat_load_dword v10, v[2:3] offset:2816 sc1
	flat_load_dword v9, v[2:3] offset:3072 sc1
	flat_load_dword v8, v[2:3] offset:3328 sc1
	flat_load_dword v7, v[2:3] offset:3584 sc1
	s_nop 0
	flat_load_dword v2, v[2:3] offset:3840 sc1
	v_mov_b64_e32 v[4:5], s[4:5]
	flat_load_dword v3, v[4:5] sc1
	v_mov_b64_e32 v[4:5], s[6:7]
	v_mov_b64_e32 v[18:19], s[8:9]
	flat_load_dword v4, v[4:5] sc1
	s_nop 0
	flat_load_dword v5, v[18:19] sc1
	v_mov_b64_e32 v[18:19], s[10:11]
	flat_load_dword v6, v[18:19] sc1
	s_waitcnt vmcnt(0) lgkmcnt(0)
	v_add_u32_e32 v18, v16, v17
	v_add_u32_e32 v18, v18, v15
	v_add_u32_e32 v18, v18, v14
	v_add_u32_e32 v18, v18, v13
	v_add_u32_e32 v18, v18, v12
	v_add_u32_e32 v18, v18, v11
	v_add_u32_e32 v18, v18, v10
	v_add_u32_e32 v18, v18, v9
	v_add_u32_e32 v18, v18, v8
	v_add_u32_e32 v18, v18, v7
	v_add_u32_e32 v18, v18, v2
	v_add_u32_e32 v18, v18, v3
	v_add_u32_e32 v18, v18, v4
	v_add_u32_e32 v18, v18, v5
	v_add_u32_e32 v18, v18, v6
	v_cmp_ne_u32_e32 vcc, s0, v18
	s_or_b64 s[20:21], s[20:21], exec
	s_or_b64 s[18:19], s[18:19], exec
	s_and_saveexec_b64 s[22:23], vcc
	s_cbranch_execz .LBB0_912
	s_and_b32 s26, s1, 0xff
	s_mov_b64 s[24:25], -1
	s_cmp_eq_u32 s26, 0
	s_mov_b64 s[28:29], -1
	s_mov_b64 s[26:27], -1
	s_sleep 0
	s_cbranch_scc1 .LBB0_916
	s_and_saveexec_b64 s[30:31], s[28:29]
	s_cbranch_execz .LBB0_911
	s_branch .LBB0_919

.LBB0_927:
	s_and_b32 s1, s0, 0xff
	s_mov_b64 s[18:19], -1
	s_cmp_lg_u32 s1, 0
	s_mov_b64 s[20:21], -1
	s_sleep 0
	s_cbranch_scc1 .LBB0_931
	v_mov_b64_e32 v[4:5], s[2:3]
	flat_load_dword v2, v[4:5] offset:512 sc1
	s_mov_b64 s[20:21], 0
	s_mov_b64 s[22:23], -1
	s_waitcnt vmcnt(0) lgkmcnt(0)
	v_cmp_eq_u32_e32 vcc, 0, v2
	s_and_saveexec_b64 s[24:25], vcc
	s_cmp_lt_u32 s0, 0x40001
	s_cselect_b64 s[20:21], -1, 0
	s_xor_b64 s[22:23], exec, -1
	s_and_b64 s[20:21], s[20:21], exec
	s_or_b64 exec, exec, s[24:25]

.LBB0_941:
	s_and_b32 s1, s0, 0xff
	s_mov_b64 s[20:21], -1
	s_cmp_lg_u32 s1, 0
	s_mov_b64 s[24:25], -1
	s_sleep 0
	s_cbranch_scc0 .LBB0_943
	s_and_saveexec_b64 s[26:27], s[24:25]
	s_cbranch_execz .LBB0_940
	s_branch .LBB0_946

.LBB0_1002:
	v_mov_b64_e32 v[2:3], s[4:5]
	flat_load_dword v17, v[2:3] offset:1024 sc1
	flat_load_dword v16, v[2:3] offset:1280 sc1
	flat_load_dword v15, v[2:3] offset:1536 sc1
	flat_load_dword v14, v[2:3] offset:1792 sc1
	flat_load_dword v13, v[2:3] offset:2048 sc1
	flat_load_dword v12, v[2:3] offset:2304 sc1
	flat_load_dword v11, v[2:3] offset:2560 sc1
	flat_load_dword v10, v[2:3] offset:2816 sc1
	flat_load_dword v9, v[2:3] offset:3072 sc1
	flat_load_dword v8, v[2:3] offset:3328 sc1
	flat_load_dword v7, v[2:3] offset:3584 sc1
	s_nop 0
	flat_load_dword v2, v[2:3] offset:3840 sc1
	v_mov_b64_e32 v[4:5], s[6:7]
	flat_load_dword v3, v[4:5] sc1
	v_mov_b64_e32 v[4:5], s[8:9]
	v_mov_b64_e32 v[18:19], s[10:11]
	flat_load_dword v4, v[4:5] sc1
	s_nop 0
	flat_load_dword v5, v[18:19] sc1
	v_mov_b64_e32 v[18:19], s[14:15]
	flat_load_dword v6, v[18:19] sc1
	s_waitcnt vmcnt(0) lgkmcnt(0)
	v_add_u32_e32 v18, v16, v17
	v_add_u32_e32 v18, v18, v15
	v_add_u32_e32 v18, v18, v14
	v_add_u32_e32 v18, v18, v13
	v_add_u32_e32 v18, v18, v12
	v_add_u32_e32 v18, v18, v11
	v_add_u32_e32 v18, v18, v10
	v_add_u32_e32 v18, v18, v9
	v_add_u32_e32 v18, v18, v8
	v_add_u32_e32 v18, v18, v7
	v_add_u32_e32 v18, v18, v2
	v_add_u32_e32 v18, v18, v3
	v_add_u32_e32 v18, v18, v4
	v_add_u32_e32 v18, v18, v5
	v_add_u32_e32 v18, v18, v6
	v_cmp_ne_u32_e32 vcc, s0, v18
	s_or_b64 s[22:23], s[22:23], exec
	s_or_b64 s[20:21], s[20:21], exec
	s_and_saveexec_b64 s[24:25], vcc
	s_cbranch_execz .LBB0_1001
	s_and_b32 s28, s1, 0xff
	s_mov_b64 s[26:27], -1
	s_cmp_eq_u32 s28, 0
	s_mov_b64 s[30:31], -1
	s_mov_b64 s[28:29], -1
	s_sleep 0
	s_cbranch_scc1 .LBB0_1005
	s_and_saveexec_b64 s[34:35], s[30:31]
	s_cbranch_execz .LBB0_1000
	s_branch .LBB0_1008

.LBB0_1016:
	s_and_b32 s1, s0, 0xff
	s_mov_b64 s[20:21], -1
	s_cmp_lg_u32 s1, 0
	s_mov_b64 s[22:23], -1
	s_sleep 0
	s_cbranch_scc1 .LBB0_1020
	v_mov_b64_e32 v[4:5], s[4:5]
	flat_load_dword v2, v[4:5] offset:512 sc1
	s_mov_b64 s[22:23], 0
	s_mov_b64 s[24:25], -1
	s_waitcnt vmcnt(0) lgkmcnt(0)
	v_cmp_eq_u32_e32 vcc, 0, v2
	s_and_saveexec_b64 s[26:27], vcc
	s_cmp_lt_u32 s0, 0x40001
	s_cselect_b64 s[22:23], -1, 0
	s_xor_b64 s[24:25], exec, -1
	s_and_b64 s[22:23], s[22:23], exec
	s_or_b64 exec, exec, s[26:27]

.LBB0_1030:
	s_and_b32 s1, s0, 0xff
	s_mov_b64 s[22:23], -1
	s_cmp_lg_u32 s1, 0
	s_mov_b64 s[26:27], -1
	s_sleep 0
	s_cbranch_scc0 .LBB0_1032
	s_and_saveexec_b64 s[28:29], s[26:27]
	s_cbranch_execz .LBB0_1029
	s_branch .LBB0_1035

.LBB0_1258:
	v_mov_b64_e32 v[2:3], s[4:5]
	flat_load_dword v17, v[2:3] offset:1024 sc1
	flat_load_dword v16, v[2:3] offset:1280 sc1
	flat_load_dword v15, v[2:3] offset:1536 sc1
	flat_load_dword v14, v[2:3] offset:1792 sc1
	flat_load_dword v13, v[2:3] offset:2048 sc1
	flat_load_dword v12, v[2:3] offset:2304 sc1
	flat_load_dword v11, v[2:3] offset:2560 sc1
	flat_load_dword v10, v[2:3] offset:2816 sc1
	flat_load_dword v9, v[2:3] offset:3072 sc1
	flat_load_dword v8, v[2:3] offset:3328 sc1
	flat_load_dword v7, v[2:3] offset:3584 sc1
	s_nop 0
	flat_load_dword v2, v[2:3] offset:3840 sc1
	v_mov_b64_e32 v[4:5], s[8:9]
	flat_load_dword v3, v[4:5] sc1
	v_mov_b64_e32 v[4:5], s[10:11]
	v_mov_b64_e32 v[18:19], s[14:15]
	flat_load_dword v4, v[4:5] sc1
	s_nop 0
	flat_load_dword v5, v[18:19] sc1
	v_mov_b64_e32 v[18:19], s[16:17]
	flat_load_dword v6, v[18:19] sc1
	s_waitcnt vmcnt(0) lgkmcnt(0)
	v_add_u32_e32 v18, v16, v17
	v_add_u32_e32 v18, v18, v15
	v_add_u32_e32 v18, v18, v14
	v_add_u32_e32 v18, v18, v13
	v_add_u32_e32 v18, v18, v12
	v_add_u32_e32 v18, v18, v11
	v_add_u32_e32 v18, v18, v10
	v_add_u32_e32 v18, v18, v9
	v_add_u32_e32 v18, v18, v8
	v_add_u32_e32 v18, v18, v7
	v_add_u32_e32 v18, v18, v2
	v_add_u32_e32 v18, v18, v3
	v_add_u32_e32 v18, v18, v4
	v_add_u32_e32 v18, v18, v5
	v_add_u32_e32 v18, v18, v6
	v_cmp_ne_u32_e32 vcc, s0, v18
	s_or_b64 s[24:25], s[24:25], exec
	s_or_b64 s[22:23], s[22:23], exec
	s_and_saveexec_b64 s[26:27], vcc
	s_cbranch_execz .LBB0_1257
	s_and_b32 s30, s1, 0xff
	s_mov_b64 s[28:29], -1
	s_cmp_eq_u32 s30, 0
	s_mov_b64 s[34:35], -1
	s_mov_b64 s[30:31], -1
	s_sleep 0
	s_cbranch_scc1 .LBB0_1261
	s_and_saveexec_b64 s[36:37], s[34:35]
	s_cbranch_execz .LBB0_1256
	s_branch .LBB0_1264

.LBB0_1272:
	s_and_b32 s1, s0, 0xff
	s_mov_b64 s[22:23], -1
	s_cmp_lg_u32 s1, 0
	s_mov_b64 s[24:25], -1
	s_sleep 0
	s_cbranch_scc1 .LBB0_1276
	v_mov_b64_e32 v[4:5], s[4:5]
	flat_load_dword v2, v[4:5] offset:512 sc1
	s_mov_b64 s[24:25], 0
	s_mov_b64 s[26:27], -1
	s_waitcnt vmcnt(0) lgkmcnt(0)
	v_cmp_eq_u32_e32 vcc, 0, v2
	s_and_saveexec_b64 s[28:29], vcc
	s_cmp_lt_u32 s0, 0x40001
	s_cselect_b64 s[24:25], -1, 0
	s_xor_b64 s[26:27], exec, -1
	s_and_b64 s[24:25], s[24:25], exec
	s_or_b64 exec, exec, s[28:29]

.LBB0_1286:
	s_and_b32 s1, s0, 0xff
	s_mov_b64 s[24:25], -1
	s_cmp_lg_u32 s1, 0
	s_mov_b64 s[28:29], -1
	s_sleep 0
	s_cbranch_scc0 .LBB0_1288
	s_and_saveexec_b64 s[30:31], s[28:29]
	s_cbranch_execz .LBB0_1285
	s_branch .LBB0_1291

.LBB0_1661:
	v_mov_b64_e32 v[2:3], s[4:5]
	flat_load_dword v17, v[2:3] offset:1024 sc1
	flat_load_dword v16, v[2:3] offset:1280 sc1
	flat_load_dword v15, v[2:3] offset:1536 sc1
	flat_load_dword v14, v[2:3] offset:1792 sc1
	flat_load_dword v13, v[2:3] offset:2048 sc1
	flat_load_dword v12, v[2:3] offset:2304 sc1
	flat_load_dword v11, v[2:3] offset:2560 sc1
	flat_load_dword v10, v[2:3] offset:2816 sc1
	flat_load_dword v9, v[2:3] offset:3072 sc1
	flat_load_dword v8, v[2:3] offset:3328 sc1
	flat_load_dword v7, v[2:3] offset:3584 sc1
	s_nop 0
	flat_load_dword v2, v[2:3] offset:3840 sc1
	v_mov_b64_e32 v[4:5], s[2:3]
	flat_load_dword v3, v[4:5] sc1
	v_mov_b64_e32 v[4:5], s[8:9]
	v_mov_b64_e32 v[18:19], s[10:11]
	flat_load_dword v4, v[4:5] sc1
	s_nop 0
	flat_load_dword v5, v[18:19] sc1
	v_mov_b64_e32 v[18:19], s[14:15]
	flat_load_dword v6, v[18:19] sc1
	s_waitcnt vmcnt(0) lgkmcnt(0)
	v_add_u32_e32 v18, v16, v17
	v_add_u32_e32 v18, v18, v15
	v_add_u32_e32 v18, v18, v14
	v_add_u32_e32 v18, v18, v13
	v_add_u32_e32 v18, v18, v12
	v_add_u32_e32 v18, v18, v11
	v_add_u32_e32 v18, v18, v10
	v_add_u32_e32 v18, v18, v9
	v_add_u32_e32 v18, v18, v8
	v_add_u32_e32 v18, v18, v7
	v_add_u32_e32 v18, v18, v2
	v_add_u32_e32 v18, v18, v3
	v_add_u32_e32 v18, v18, v4
	v_add_u32_e32 v18, v18, v5
	v_add_u32_e32 v18, v18, v6
	v_cmp_ne_u32_e32 vcc, s0, v18
	s_or_b64 s[22:23], s[22:23], exec
	s_or_b64 s[20:21], s[20:21], exec
	s_and_saveexec_b64 s[24:25], vcc
	s_cbranch_execz .LBB0_1660
	s_and_b32 s28, s1, 0xff
	s_mov_b64 s[26:27], -1
	s_cmp_eq_u32 s28, 0
	s_mov_b64 s[30:31], -1
	s_mov_b64 s[28:29], -1
	s_sleep 0
	s_cbranch_scc1 .LBB0_1664
	s_and_saveexec_b64 s[34:35], s[30:31]
	s_cbranch_execz .LBB0_1659
	s_branch .LBB0_1667
